# up-proj GEMM epilogue rewritten by hand: A rows staged permuted (LDS row 16m+fr <- seg row 4fr+m) so conv neighbours are in-lane; fused fma/dpp; half the VALU
# speedup vs baseline: 1.0355x; 1.0355x over previous
.LBB0_90:
	s_andn2_b64 vcc, exec, s[2:3]
	s_cbranch_vccnz .LBB0_143
	v_ashrrev_i32_e32 v2, 31, v3
	v_lshrrev_b32_e32 v2, 26, v2
	v_add_u32_e32 v2, v3, v2
	v_ashrrev_i32_e32 v5, 6, v2
	v_bfe_i32 v2, v3, 27, 1
	v_lshlrev_b32_e32 v0, 4, v3
	v_lshrrev_b32_e32 v2, 22, v2
	v_add_u32_e32 v2, v0, v2
	v_and_b32_e32 v2, 0xfffffc00, v2
	v_sub_u32_e32 v2, v0, v2
	v_lshrrev_b32_e32 v4, 4, v2
	v_bitop3_b32 v4, v4, v2, 32 bitop3:0x6c
	v_ashrrev_i32_e32 v2, 31, v2
	v_lshrrev_b32_e32 v2, 26, v2
	v_lshlrev_b32_e32 v6, 3, v5
	v_add_u32_e32 v2, v4, v2
	v_and_b32_e32 v6, -16, v6
	v_ashrrev_i32_e32 v2, 6, v2
	v_add_u32_e32 v8, v2, v6
	v_mul_i32_i24_e32 v2, 64, v2
	v_sub_u32_e32 v2, v4, v2
	v_lshlrev_b32_e32 v6, 5, v5
	v_ashrrev_i16_sdwa v2, v206, sext(v2) dst_sel:DWORD dst_unused:UNUSED_PAD src0_sel:DWORD src1_sel:BYTE_0
	v_and_b32_e32 v10, 32, v6
	v_bfe_i32 v14, v2, 0, 16
	v_lshrrev_b32_e32 v15, 6, v8
	v_and_b32_e32 v2, 63, v8
	v_lshlrev_b32_e32 v20, 2, v2
	v_lshrrev_b32_e32 v2, 4, v2
	v_and_or_b32 v2, v20, 60, v2
	v_mad_u64_u32 v[6:7], s[34:35], v15, 62, v[2:3]
	v_add_lshl_u32 v4, v10, v14, 1
	v_add_u32_e32 v0, 0x2000, v0
	v_lshl_add_u32 v162, v6, 11, v4
	v_lshl_add_u32 v10, v8, 11, v4
	v_ashrrev_i32_e32 v4, 31, v0
	v_lshrrev_b32_e32 v4, 22, v4
	v_add_u32_e32 v4, v0, v4
	v_ashrrev_i32_e32 v16, 10, v4
	v_mul_i32_i24_e32 v4, 0x400, v16
	v_sub_u32_e32 v0, v0, v4
	v_lshrrev_b32_e32 v4, 4, v0
	v_bitop3_b32 v0, v4, v0, 32 bitop3:0x6c
	v_ashrrev_i32_e32 v6, 31, v0
	v_lshrrev_b32_e32 v6, 26, v6
	v_lshlrev_b32_e32 v4, 3, v16
	v_add_u32_e32 v6, v0, v6
	s_mul_i32 s2, s62, 0x10800
	v_and_b32_e32 v4, -16, v4
	v_ashrrev_i32_e32 v7, 6, v6
	s_mul_hi_i32 s1, s62, 0x10800
	s_add_u32 s22, s86, s2
	v_add_u32_e32 v8, v7, v4
	v_lshlrev_b32_e32 v4, 5, v16
	s_addc_u32 s23, s87, s1
	s_mul_i32 s2, s62, 0x5800
	v_and_b32_e32 v11, 32, v4
	v_and_b32_e32 v4, 0xc0, v6
	s_mul_hi_i32 s1, s62, 0x5800
	s_add_u32 s12, s88, s2
	v_sub_u32_e32 v0, v0, v4
	s_addc_u32 s1, s89, s1
	s_mul_i32 s3, s62, 0x1880000
	v_ashrrev_i16_sdwa v0, v206, sext(v0) dst_sel:DWORD dst_unused:UNUSED_PAD src0_sel:DWORD src1_sel:BYTE_0
	s_mul_hi_i32 s2, s62, 0x1880000
	s_add_u32 s3, s8, s3
	v_bfe_i32 v17, v0, 0, 16
	s_addc_u32 s2, s9, s2
	v_lshrrev_b32_e32 v18, 6, v8
	v_and_b32_e32 v4, 63, v8
	v_lshlrev_b32_e32 v19, 2, v4
	v_lshrrev_b32_e32 v4, 4, v4
	v_and_or_b32 v4, v19, 60, v4
	v_add_lshl_u32 v0, v11, v17, 1
	s_add_u32 s90, s3, 0x804000
	v_mad_u64_u32 v[6:7], s[34:35], v18, 62, v[4:5]
	v_lshl_add_u32 v166, v8, 11, v0
	v_bfe_u32 v8, v3, 3, 2
	s_addc_u32 s77, s2, 0
	s_ashr_i32 s13, s64, 6
	v_lshl_add_u32 v164, v6, 11, v0
	v_mul_u32_u24_e32 v0, 0x1600, v8
	s_lshl_b32 s78, s13, 10
	v_lshlrev_b32_e32 v0, 2, v0
	v_lshl_add_u64 v[6:7], s[22:23], 0, v[0:1]
	v_mov_b32_e32 v0, s1
	v_cmp_eq_u32_e32 vcc, 3, v8
	s_add_i32 s85, s78, 0
	s_mul_i32 s1, s50, 0xf8
	s_and_b32 s2, s13, 3
	s_ashr_i32 s3, s64, 8
	v_cndmask_b32_e32 v7, v7, v0, vcc
	v_mov_b32_e32 v0, s12
	s_add_i32 s88, s85, 0x21400
	s_add_i32 s12, s1, 0xffffff1a
	s_cmpk_lt_i32 s50, 0x43
	v_and_b32_e32 v19, 4, v3
	s_cselect_b32 s22, s1, s12
	v_cndmask_b32_e32 v6, v6, v0, vcc
	v_lshl_or_b32 v0, s0, 3, v19
	v_lshlrev_b32_e32 v20, 2, v3
	s_ashr_i32 s23, s22, 31
	v_and_b32_e32 v9, 63, v3
	v_or_b32_e32 v0, s2, v0
	v_and_b32_e32 v176, 12, v20
	s_lshl_b64 s[22:23], s[22:23], 11
	v_readlane_b32 s12, v252, 20
	v_lshl_or_b32 v8, v0, 4, v176
	v_cmp_lt_u32_e32 vcc, 31, v9
	v_mov_b32_e32 v0, 0x2c00
	v_readlane_b32 s13, v252, 21
	s_add_u32 s34, s12, s22
	v_cndmask_b32_e32 v0, 0, v0, vcc
	s_addc_u32 s35, s13, s23
	s_ashr_i32 s1, s0, 31
	v_lshl_add_u64 v[168:169], v[6:7], 0, v[0:1]
	v_ashrrev_i32_e32 v9, 31, v8
	s_lshl_b64 s[22:23], s[0:1], 19
	v_lshl_add_u64 v[6:7], v[8:9], 2, v[168:169]
	s_mov_b32 m0, s88
	s_add_u32 s48, s90, s22
	global_load_lds_dwordx4 v[6:7], off
	s_addc_u32 s49, s77, s23
	s_add_i32 m0, s85, 0x10000
	s_add_i32 s82, s85, 0x2000
	global_load_lds_dwordx4 v10, s[48:49]
	s_add_i32 m0, s85, 0x12000
	s_add_u32 s22, s48, 0x40000
	global_load_lds_dwordx4 v166, s[48:49]
	s_mov_b32 m0, s85
	s_addc_u32 s23, s49, 0
	global_load_lds_dwordx4 v162, s[34:35]
	s_mov_b32 m0, s82
	v_mov_b32_e32 v0, v10
	global_load_lds_dwordx4 v164, s[34:35]
	s_add_i32 m0, s85, 0x14000
	v_mov_b32_e32 v167, v1
	global_load_lds_dwordx4 v10, s[22:23]
	s_add_i32 m0, s85, 0x16000
	v_mov_b32_e32 v163, v1
	global_load_lds_dwordx4 v166, s[22:23]
	s_add_u32 s22, s34, 0x3e000
	s_addc_u32 s23, s35, 0
	s_add_i32 s89, s85, 0x4000
	s_mov_b32 m0, s89
	s_add_i32 s91, s85, 0x6000
	global_load_lds_dwordx4 v162, s[22:23]
	s_mov_b32 m0, s91
	v_mov_b32_e32 v165, v1
	global_load_lds_dwordx4 v164, s[22:23]
	v_lshl_add_u64 v[12:13], s[48:49], 0, v[0:1]
	v_lshl_add_u64 v[10:11], s[48:49], 0, v[166:167]
	v_lshl_add_u64 v[8:9], s[34:35], 0, v[162:163]
	s_cmp_lg_u32 s3, 1
	v_lshl_add_u64 v[6:7], s[34:35], 0, v[164:165]
	s_cbranch_scc1 .LBB0_93
	s_barrier

.LBB0_104:
	s_add_u32 s2, s34, 0xfffc2080
	s_addc_u32 s3, s35, -1
	s_add_i32 s12, 0, 0x10000
	v_add_u32_e32 v110, s12, v179
	ds_read_b128 v[98:101], v110
	ds_read_b128 v[102:105], v110 offset:1024
	ds_read_b128 v[106:109], v110 offset:2048
	ds_read_b128 v[110:113], v110 offset:3072
	s_cmp_eq_u32 s53, 12
	s_cselect_b32 s49, s97, s3
	s_cselect_b32 s48, s96, s2
	s_cselect_b32 s3, s1, s52
	s_cselect_b32 s2, s23, s51
	v_lshl_add_u64 v[174:175], s[34:35], 0, v[170:171]
	s_add_i32 m0, s85, 0xc000
	ds_read_b128 v[114:117], v184
	ds_read_b128 v[118:121], v184 offset:1024
	ds_read_b128 v[122:125], v184 offset:2048
	ds_read_b128 v[126:129], v184 offset:3072
	ds_read_b128 v[186:189], v184 offset:4096
	ds_read_b128 v[190:193], v184 offset:5120
	ds_read_b128 v[194:197], v184 offset:6144
	ds_read_b128 v[198:201], v184 offset:7168
	global_load_lds_dwordx4 v[174:175], off
	v_lshl_add_u64 v[174:175], s[34:35], 0, v[172:173]
	s_add_i32 m0, s85, 0xe000
	s_nop 0
	global_load_lds_dwordx4 v[174:175], off
	s_waitcnt lgkmcnt(8)
	s_barrier
	s_waitcnt lgkmcnt(0)
	s_setprio 1
	s_waitcnt lgkmcnt(0)
	v_mfma_f32_16x16x32_bf16 v[158:161], v[98:101], v[114:117], v[158:161]
	v_mfma_f32_16x16x32_bf16 v[154:157], v[106:109], v[114:117], v[154:157]
	v_mfma_f32_16x16x32_bf16 v[150:153], v[98:101], v[122:125], v[150:153]
	v_mfma_f32_16x16x32_bf16 v[146:149], v[106:109], v[122:125], v[146:149]
	v_mfma_f32_16x16x32_bf16 v[142:145], v[98:101], v[186:189], v[142:145]
	v_mfma_f32_16x16x32_bf16 v[138:141], v[106:109], v[186:189], v[138:141]
	v_mfma_f32_16x16x32_bf16 v[134:137], v[98:101], v[194:197], v[134:137]
	v_mfma_f32_16x16x32_bf16 v[130:133], v[106:109], v[194:197], v[130:133]
	v_mfma_f32_16x16x32_bf16 v[158:161], v[102:105], v[118:121], v[158:161]
	v_mfma_f32_16x16x32_bf16 v[154:157], v[110:113], v[118:121], v[154:157]
	v_mfma_f32_16x16x32_bf16 v[150:153], v[102:105], v[126:129], v[150:153]
	v_mfma_f32_16x16x32_bf16 v[146:149], v[110:113], v[126:129], v[146:149]
	v_mfma_f32_16x16x32_bf16 v[142:145], v[102:105], v[190:193], v[142:145]
	v_mfma_f32_16x16x32_bf16 v[138:141], v[110:113], v[190:193], v[138:141]
	v_mfma_f32_16x16x32_bf16 v[134:137], v[102:105], v[198:201], v[134:137]
	v_mfma_f32_16x16x32_bf16 v[130:133], v[110:113], v[198:201], v[130:133]
	s_setprio 0
	s_barrier
	s_add_i32 s54, 0, 0x14000
	v_add_u32_e32 v174, s54, v179
	s_add_i32 s12, s12, s78
	ds_read_b128 v[226:229], v174
	ds_read_b128 v[230:233], v174 offset:1024
	ds_read_b128 v[234:237], v174 offset:2048
	ds_read_b128 v[242:245], v174 offset:3072
	v_lshl_add_u64 v[174:175], s[2:3], 0, v[0:1]
	s_mov_b32 m0, s12
	v_lshl_add_u64 v[246:247], s[2:3], 0, v[166:167]
	global_load_lds_dwordx4 v[174:175], off
	s_add_i32 m0, s12, 0x2000
	s_nop 0
	global_load_lds_dwordx4 v[246:247], off
	s_barrier
	s_waitcnt lgkmcnt(0)
	s_setprio 1
	s_waitcnt lgkmcnt(0)
	v_mfma_f32_16x16x32_bf16 v[62:65], v[226:229], v[114:117], v[62:65]
	v_mfma_f32_16x16x32_bf16 v[58:61], v[234:237], v[114:117], v[58:61]
	v_mfma_f32_16x16x32_bf16 v[54:57], v[226:229], v[122:125], v[54:57]
	v_mfma_f32_16x16x32_bf16 v[50:53], v[234:237], v[122:125], v[50:53]
	v_mfma_f32_16x16x32_bf16 v[46:49], v[226:229], v[186:189], v[46:49]
	v_mfma_f32_16x16x32_bf16 v[42:45], v[234:237], v[186:189], v[42:45]
	v_mfma_f32_16x16x32_bf16 v[38:41], v[226:229], v[194:197], v[38:41]
	v_mfma_f32_16x16x32_bf16 v[34:37], v[234:237], v[194:197], v[34:37]
	v_mfma_f32_16x16x32_bf16 v[62:65], v[230:233], v[118:121], v[62:65]
	v_mfma_f32_16x16x32_bf16 v[58:61], v[242:245], v[118:121], v[58:61]
	v_mfma_f32_16x16x32_bf16 v[54:57], v[230:233], v[126:129], v[54:57]
	v_mfma_f32_16x16x32_bf16 v[50:53], v[242:245], v[126:129], v[50:53]
	v_mfma_f32_16x16x32_bf16 v[46:49], v[230:233], v[190:193], v[46:49]
	v_mfma_f32_16x16x32_bf16 v[42:45], v[242:245], v[190:193], v[42:45]
	v_mfma_f32_16x16x32_bf16 v[38:41], v[230:233], v[198:201], v[38:41]
	v_mfma_f32_16x16x32_bf16 v[34:37], v[242:245], v[198:201], v[34:37]
	s_setprio 0
	s_mov_b32 m0, s85
	v_lshl_add_u64 v[248:249], s[48:49], 0, v[162:163]
	s_barrier
	ds_read_b128 v[114:117], v184 offset:16384
	ds_read_b128 v[118:121], v184 offset:17408
	ds_read_b128 v[122:125], v184 offset:18432
	ds_read_b128 v[126:129], v184 offset:19456
	ds_read_b128 v[186:189], v184 offset:20480
	ds_read_b128 v[190:193], v184 offset:21504
	ds_read_b128 v[194:197], v184 offset:22528
	ds_read_b128 v[198:201], v184 offset:23552
	global_load_lds_dwordx4 v[248:249], off
	v_lshl_add_u64 v[250:251], s[48:49], 0, v[164:165]
	s_mov_b32 m0, s82
	s_nop 0
	global_load_lds_dwordx4 v[250:251], off
	s_barrier
	s_waitcnt lgkmcnt(0)
	s_setprio 1
	s_waitcnt lgkmcnt(0)
	v_mfma_f32_16x16x32_bf16 v[94:97], v[98:101], v[114:117], v[94:97]
	v_mfma_f32_16x16x32_bf16 v[90:93], v[106:109], v[114:117], v[90:93]
	v_mfma_f32_16x16x32_bf16 v[86:89], v[98:101], v[122:125], v[86:89]
	v_mfma_f32_16x16x32_bf16 v[82:85], v[106:109], v[122:125], v[82:85]
	v_mfma_f32_16x16x32_bf16 v[78:81], v[98:101], v[186:189], v[78:81]
	v_mfma_f32_16x16x32_bf16 v[74:77], v[106:109], v[186:189], v[74:77]
	v_mfma_f32_16x16x32_bf16 v[70:73], v[98:101], v[194:197], v[70:73]
	v_mfma_f32_16x16x32_bf16 v[66:69], v[106:109], v[194:197], v[66:69]
	v_mfma_f32_16x16x32_bf16 v[94:97], v[102:105], v[118:121], v[94:97]
	v_mfma_f32_16x16x32_bf16 v[90:93], v[110:113], v[118:121], v[90:93]
	v_mfma_f32_16x16x32_bf16 v[86:89], v[102:105], v[126:129], v[86:89]
	v_mfma_f32_16x16x32_bf16 v[82:85], v[110:113], v[126:129], v[82:85]
	v_mfma_f32_16x16x32_bf16 v[78:81], v[102:105], v[190:193], v[78:81]
	v_mfma_f32_16x16x32_bf16 v[74:77], v[110:113], v[190:193], v[74:77]
	v_mfma_f32_16x16x32_bf16 v[70:73], v[102:105], v[198:201], v[70:73]
	v_mfma_f32_16x16x32_bf16 v[66:69], v[110:113], v[198:201], v[66:69]
	s_setprio 0
	s_barrier
	s_add_u32 s12, s2, 0x40000
	s_addc_u32 s13, s3, 0
	s_add_i32 s54, s54, s78
	v_lshl_add_u64 v[98:99], s[12:13], 0, v[0:1]
	s_mov_b32 m0, s54
	s_nop 0
	global_load_lds_dwordx4 v[98:99], off
	v_lshl_add_u64 v[98:99], s[12:13], 0, v[166:167]
	s_add_i32 m0, s54, 0x2000
	s_nop 0
	global_load_lds_dwordx4 v[98:99], off
	s_waitcnt vmcnt(6)
	s_barrier
	s_setprio 1
	v_mfma_f32_16x16x32_bf16 v[30:33], v[226:229], v[114:117], v[30:33]
	v_mfma_f32_16x16x32_bf16 v[26:29], v[234:237], v[114:117], v[26:29]
	v_mfma_f32_16x16x32_bf16 v[22:25], v[226:229], v[122:125], v[22:25]
	v_mfma_f32_16x16x32_bf16 v[18:21], v[234:237], v[122:125], v[18:21]
	v_mfma_f32_16x16x32_bf16 v[14:17], v[226:229], v[186:189], v[14:17]
	v_mfma_f32_16x16x32_bf16 v[10:13], v[234:237], v[186:189], v[10:13]
	v_mfma_f32_16x16x32_bf16 v[6:9], v[226:229], v[194:197], v[6:9]
	v_mfma_f32_16x16x32_bf16 v[2:5], v[234:237], v[194:197], v[2:5]
	v_mfma_f32_16x16x32_bf16 v[30:33], v[230:233], v[118:121], v[30:33]
	v_mfma_f32_16x16x32_bf16 v[26:29], v[242:245], v[118:121], v[26:29]
	v_mfma_f32_16x16x32_bf16 v[22:25], v[230:233], v[126:129], v[22:25]
	v_mfma_f32_16x16x32_bf16 v[18:21], v[242:245], v[126:129], v[18:21]
	v_mfma_f32_16x16x32_bf16 v[14:17], v[230:233], v[190:193], v[14:17]
	v_mfma_f32_16x16x32_bf16 v[10:13], v[242:245], v[190:193], v[10:13]
	v_mfma_f32_16x16x32_bf16 v[6:9], v[230:233], v[198:201], v[6:9]
	v_mfma_f32_16x16x32_bf16 v[2:5], v[242:245], v[198:201], v[2:5]
	s_setprio 0
	s_add_i32 s54, 0, 0x18000
	v_add_u32_e32 v110, s54, v179
	s_barrier
	ds_read_b128 v[98:101], v110
	ds_read_b128 v[102:105], v110 offset:1024
	ds_read_b128 v[106:109], v110 offset:2048
	ds_read_b128 v[110:113], v110 offset:3072
	s_add_u32 s12, s48, 0x3e000
	s_addc_u32 s13, s49, 0
	s_mov_b32 m0, s89
	v_lshl_add_u64 v[226:227], s[12:13], 0, v[162:163]
	ds_read_b128 v[114:117], v184 offset:32768
	ds_read_b128 v[118:121], v184 offset:33792
	ds_read_b128 v[122:125], v184 offset:34816
	ds_read_b128 v[126:129], v184 offset:35840
	ds_read_b128 v[186:189], v184 offset:36864
	ds_read_b128 v[190:193], v184 offset:37888
	ds_read_b128 v[194:197], v184 offset:38912
	ds_read_b128 v[198:201], v184 offset:39936
	global_load_lds_dwordx4 v[226:227], off
	v_lshl_add_u64 v[226:227], s[12:13], 0, v[164:165]
	s_mov_b32 m0, s91
	s_nop 0
	global_load_lds_dwordx4 v[226:227], off
	s_waitcnt lgkmcnt(8)
	s_barrier
	s_waitcnt lgkmcnt(0)
	s_setprio 1
	s_waitcnt lgkmcnt(0)
	v_mfma_f32_16x16x32_bf16 v[158:161], v[98:101], v[114:117], v[158:161]
	v_mfma_f32_16x16x32_bf16 v[154:157], v[106:109], v[114:117], v[154:157]
	v_mfma_f32_16x16x32_bf16 v[150:153], v[98:101], v[122:125], v[150:153]
	v_mfma_f32_16x16x32_bf16 v[146:149], v[106:109], v[122:125], v[146:149]
	v_mfma_f32_16x16x32_bf16 v[142:145], v[98:101], v[186:189], v[142:145]
	v_mfma_f32_16x16x32_bf16 v[138:141], v[106:109], v[186:189], v[138:141]
	v_mfma_f32_16x16x32_bf16 v[134:137], v[98:101], v[194:197], v[134:137]
	v_mfma_f32_16x16x32_bf16 v[130:133], v[106:109], v[194:197], v[130:133]
	v_mfma_f32_16x16x32_bf16 v[158:161], v[102:105], v[118:121], v[158:161]
	v_mfma_f32_16x16x32_bf16 v[154:157], v[110:113], v[118:121], v[154:157]
	v_mfma_f32_16x16x32_bf16 v[150:153], v[102:105], v[126:129], v[150:153]
	v_mfma_f32_16x16x32_bf16 v[146:149], v[110:113], v[126:129], v[146:149]
	v_mfma_f32_16x16x32_bf16 v[142:145], v[102:105], v[190:193], v[142:145]
	v_mfma_f32_16x16x32_bf16 v[138:141], v[110:113], v[190:193], v[138:141]
	v_mfma_f32_16x16x32_bf16 v[134:137], v[102:105], v[198:201], v[134:137]
	v_mfma_f32_16x16x32_bf16 v[130:133], v[110:113], v[198:201], v[130:133]
	s_setprio 0
	s_barrier
	s_add_i32 s12, 0, 0x1c000
	s_add_i32 s13, s54, s78
	v_add_u32_e32 v242, s12, v179
	v_lshl_add_u64 v[174:175], v[174:175], 0, s[20:21]
	s_mov_b32 m0, s13
	ds_read_b128 v[226:229], v242
	ds_read_b128 v[230:233], v242 offset:1024
	ds_read_b128 v[234:237], v242 offset:2048
	ds_read_b128 v[242:245], v242 offset:3072
	global_load_lds_dwordx4 v[174:175], off
	v_lshl_add_u64 v[174:175], v[246:247], 0, s[20:21]
	s_add_i32 m0, s13, 0x2000
	s_nop 0
	global_load_lds_dwordx4 v[174:175], off
	s_barrier
	s_waitcnt lgkmcnt(0)
	s_setprio 1
	s_waitcnt lgkmcnt(0)
	v_mfma_f32_16x16x32_bf16 v[62:65], v[226:229], v[114:117], v[62:65]
	v_mfma_f32_16x16x32_bf16 v[58:61], v[234:237], v[114:117], v[58:61]
	v_mfma_f32_16x16x32_bf16 v[54:57], v[226:229], v[122:125], v[54:57]
	v_mfma_f32_16x16x32_bf16 v[50:53], v[234:237], v[122:125], v[50:53]
	v_mfma_f32_16x16x32_bf16 v[46:49], v[226:229], v[186:189], v[46:49]
	v_mfma_f32_16x16x32_bf16 v[42:45], v[234:237], v[186:189], v[42:45]
	v_mfma_f32_16x16x32_bf16 v[38:41], v[226:229], v[194:197], v[38:41]
	v_mfma_f32_16x16x32_bf16 v[34:37], v[234:237], v[194:197], v[34:37]
	v_mfma_f32_16x16x32_bf16 v[62:65], v[230:233], v[118:121], v[62:65]
	v_mfma_f32_16x16x32_bf16 v[58:61], v[242:245], v[118:121], v[58:61]
	v_mfma_f32_16x16x32_bf16 v[54:57], v[230:233], v[126:129], v[54:57]
	v_mfma_f32_16x16x32_bf16 v[50:53], v[242:245], v[126:129], v[50:53]
	v_mfma_f32_16x16x32_bf16 v[46:49], v[230:233], v[190:193], v[46:49]
	v_mfma_f32_16x16x32_bf16 v[42:45], v[242:245], v[190:193], v[42:45]
	v_mfma_f32_16x16x32_bf16 v[38:41], v[230:233], v[198:201], v[38:41]
	v_mfma_f32_16x16x32_bf16 v[34:37], v[242:245], v[198:201], v[34:37]
	s_setprio 0
	s_mov_b32 m0, s79
	v_lshl_add_u64 v[174:175], v[248:249], 0, s[20:21]
	s_barrier
	ds_read_b128 v[114:117], v184 offset:49152
	ds_read_b128 v[118:121], v184 offset:50176
	ds_read_b128 v[122:125], v184 offset:51200
	ds_read_b128 v[126:129], v184 offset:52224
	ds_read_b128 v[186:189], v184 offset:53248
	ds_read_b128 v[190:193], v184 offset:54272
	ds_read_b128 v[194:197], v184 offset:55296
	ds_read_b128 v[198:201], v184 offset:56320
	global_load_lds_dwordx4 v[174:175], off
	v_lshl_add_u64 v[174:175], v[250:251], 0, s[20:21]
	s_mov_b32 m0, s87
	s_nop 0
	global_load_lds_dwordx4 v[174:175], off
	s_barrier
	s_waitcnt lgkmcnt(0)
	s_setprio 1
	s_waitcnt lgkmcnt(0)
	v_mfma_f32_16x16x32_bf16 v[94:97], v[98:101], v[114:117], v[94:97]
	v_mfma_f32_16x16x32_bf16 v[90:93], v[106:109], v[114:117], v[90:93]
	v_mfma_f32_16x16x32_bf16 v[86:89], v[98:101], v[122:125], v[86:89]
	v_mfma_f32_16x16x32_bf16 v[82:85], v[106:109], v[122:125], v[82:85]
	v_mfma_f32_16x16x32_bf16 v[78:81], v[98:101], v[186:189], v[78:81]
	v_mfma_f32_16x16x32_bf16 v[74:77], v[106:109], v[186:189], v[74:77]
	v_mfma_f32_16x16x32_bf16 v[70:73], v[98:101], v[194:197], v[70:73]
	v_mfma_f32_16x16x32_bf16 v[66:69], v[106:109], v[194:197], v[66:69]
	v_mfma_f32_16x16x32_bf16 v[94:97], v[102:105], v[118:121], v[94:97]
	v_mfma_f32_16x16x32_bf16 v[90:93], v[110:113], v[118:121], v[90:93]
	v_mfma_f32_16x16x32_bf16 v[86:89], v[102:105], v[126:129], v[86:89]
	v_mfma_f32_16x16x32_bf16 v[82:85], v[110:113], v[126:129], v[82:85]
	v_mfma_f32_16x16x32_bf16 v[78:81], v[102:105], v[190:193], v[78:81]
	v_mfma_f32_16x16x32_bf16 v[74:77], v[110:113], v[190:193], v[74:77]
	v_mfma_f32_16x16x32_bf16 v[70:73], v[102:105], v[198:201], v[70:73]
	v_mfma_f32_16x16x32_bf16 v[66:69], v[110:113], v[198:201], v[66:69]
	s_setprio 0
	s_barrier
	s_add_u32 s2, s2, 0x40080
	s_addc_u32 s3, s3, 0
	s_add_i32 s12, s12, s78
	v_lshl_add_u64 v[98:99], s[2:3], 0, v[0:1]
	s_mov_b32 m0, s12
	s_nop 0
	global_load_lds_dwordx4 v[98:99], off
	v_lshl_add_u64 v[98:99], s[2:3], 0, v[166:167]
	s_add_i32 m0, s12, 0x2000
	s_nop 0
	global_load_lds_dwordx4 v[98:99], off
	s_waitcnt vmcnt(6)
	s_barrier
	s_setprio 1
	v_mfma_f32_16x16x32_bf16 v[30:33], v[226:229], v[114:117], v[30:33]
	v_mfma_f32_16x16x32_bf16 v[26:29], v[234:237], v[114:117], v[26:29]
	v_mfma_f32_16x16x32_bf16 v[22:25], v[226:229], v[122:125], v[22:25]
	v_mfma_f32_16x16x32_bf16 v[18:21], v[234:237], v[122:125], v[18:21]
	v_mfma_f32_16x16x32_bf16 v[14:17], v[226:229], v[186:189], v[14:17]
	v_mfma_f32_16x16x32_bf16 v[10:13], v[234:237], v[186:189], v[10:13]
	v_mfma_f32_16x16x32_bf16 v[6:9], v[226:229], v[194:197], v[6:9]
	v_mfma_f32_16x16x32_bf16 v[2:5], v[234:237], v[194:197], v[2:5]
	v_mfma_f32_16x16x32_bf16 v[30:33], v[230:233], v[118:121], v[30:33]
	v_mfma_f32_16x16x32_bf16 v[26:29], v[242:245], v[118:121], v[26:29]
	v_mfma_f32_16x16x32_bf16 v[22:25], v[230:233], v[126:129], v[22:25]
	v_mfma_f32_16x16x32_bf16 v[18:21], v[242:245], v[126:129], v[18:21]
	v_mfma_f32_16x16x32_bf16 v[14:17], v[230:233], v[190:193], v[14:17]
	v_mfma_f32_16x16x32_bf16 v[10:13], v[242:245], v[190:193], v[10:13]
	v_mfma_f32_16x16x32_bf16 v[6:9], v[230:233], v[198:201], v[6:9]
	v_mfma_f32_16x16x32_bf16 v[2:5], v[242:245], v[198:201], v[2:5]
	s_setprio 0
	s_add_i32 s53, s53, 2
	s_add_u32 s34, s34, 0x100
	s_addc_u32 s35, s35, 0
	s_add_u32 s51, s51, 0x100
	s_addc_u32 s52, s52, 0
	s_cmp_gt_u32 s53, 13
	s_barrier
	s_cbranch_scc0 .LBB0_104
	s_add_i32 s1, s50, 0xffffffbd
	s_cmpk_gt_i32 s50, 0x42
	s_cselect_b32 s1, s1, s50
	s_mul_i32 s23, s1, 0xf8
	s_cselect_b32 s2, 0x4000, 0
	s_cselect_b32 s3, 0x100, s37
	s_add_i32 s23, s23, s84
	v_add_u32_e32 v188, s88, v178
	ds_read_b128 v[126:129], v188
	ds_read_b128 v[122:125], v188 offset:128
	ds_read_b128 v[114:117], v188 offset:256
	ds_read_b128 v[118:121], v188 offset:384
	ds_read_b128 v[110:113], v188 offset:512
	ds_read_b128 v[106:109], v188 offset:640
	ds_read_b128 v[98:101], v188 offset:768
	ds_read_b128 v[102:105], v188 offset:896
	v_readlane_b32 s12, v252, 28
	v_readlane_b32 s13, v252, 29
	v_lshl_or_b32 v174, s0, 7, v180
	v_lshl_add_u32 v186, v177, 2, s23
	v_add_u32_e32 v187, s2, v186
	v_mul_u32_u24_e32 v187, 0x1600, v187
	v_lshl_add_u32 v187, v174, 1, v187
	s_waitcnt lgkmcnt(0)
	v_fma_f32 v190, v158, v122, v118
	v_fma_f32 v191, v159, v123, v119
	v_fma_f32 v192, v160, v124, v120
	v_fma_f32 v193, v161, v125, v121
	v_fma_f32 v194, v154, v106, v102
	v_fma_f32 v195, v155, v107, v103
	v_fma_f32 v196, v156, v108, v104
	v_fma_f32 v197, v157, v109, v105
	v_add_u32_e32 v228, 0, v186
	v_fmac_f32_dpp v190, v134, v126 row_ror:1 row_mask:0xf bank_mask:0xf
	v_fmac_f32_dpp v191, v135, v127 row_ror:1 row_mask:0xf bank_mask:0xf
	v_fmac_f32_dpp v192, v136, v128 row_ror:1 row_mask:0xf bank_mask:0xf
	v_fmac_f32_dpp v193, v137, v129 row_ror:1 row_mask:0xf bank_mask:0xf
	v_fmac_f32_dpp v194, v130, v110 row_ror:1 row_mask:0xf bank_mask:0xf
	v_fmac_f32_dpp v195, v131, v111 row_ror:1 row_mask:0xf bank_mask:0xf
	v_fmac_f32_dpp v196, v132, v112 row_ror:1 row_mask:0xf bank_mask:0xf
	v_fmac_f32_dpp v197, v133, v113 row_ror:1 row_mask:0xf bank_mask:0xf
	v_fmac_f32_e32 v190, v150, v114
	v_fmac_f32_e32 v191, v151, v115
	v_fmac_f32_e32 v192, v152, v116
	v_fmac_f32_e32 v193, v153, v117
	v_fmac_f32_e32 v194, v146, v98
	v_fmac_f32_e32 v195, v147, v99
	v_fmac_f32_e32 v196, v148, v100
	v_fmac_f32_e32 v197, v149, v101
	v_cmp_gt_i32_e32 vcc, s3, v228
	v_mul_f32_e32 v198, 0xbfb8aa3b, v190
	v_mul_f32_e32 v199, 0xbfb8aa3b, v191
	v_mul_f32_e32 v200, 0xbfb8aa3b, v192
	v_mul_f32_e32 v201, 0xbfb8aa3b, v193
	v_exp_f32_e32 v198, v198
	v_exp_f32_e32 v199, v199
	v_exp_f32_e32 v200, v200
	v_exp_f32_e32 v201, v201
	v_add_f32_e32 v198, 1.0, v198
	v_add_f32_e32 v199, 1.0, v199
	v_add_f32_e32 v200, 1.0, v200
	v_add_f32_e32 v201, 1.0, v201
	v_rcp_f32_e32 v198, v198
	v_rcp_f32_e32 v199, v199
	v_rcp_f32_e32 v200, v200
	v_rcp_f32_e32 v201, v201
	v_mul_f32_e32 v190, v190, v198
	v_mul_f32_e32 v191, v191, v199
	v_mul_f32_e32 v192, v192, v200
	v_mul_f32_e32 v193, v193, v201
	v_mul_f32_e32 v190, v190, v194
	v_mul_f32_e32 v191, v191, v195
	v_mul_f32_e32 v192, v192, v196
	v_mul_f32_e32 v193, v193, v197
	v_cvt_pk_bf16_f32 v226, v190, v191
	v_cvt_pk_bf16_f32 v227, v192, v193
	s_and_b64 vcc, vcc, s[42:43]
	s_and_saveexec_b64 s[0:1], vcc
	global_store_dwordx2 v187, v[226:227], s[12:13]
	s_mov_b64 exec, s[0:1]
	v_fma_f32 v190, v150, v122, v118
	v_fma_f32 v191, v151, v123, v119
	v_fma_f32 v192, v152, v124, v120
	v_fma_f32 v193, v153, v125, v121
	v_fma_f32 v194, v146, v106, v102
	v_fma_f32 v195, v147, v107, v103
	v_fma_f32 v196, v148, v108, v104
	v_fma_f32 v197, v149, v109, v105
	v_add_u32_e32 v228, 1, v186
	v_add_u32_e32 v229, 0x1600, v187
	v_fmac_f32_e32 v190, v158, v126
	v_fmac_f32_e32 v191, v159, v127
	v_fmac_f32_e32 v192, v160, v128
	v_fmac_f32_e32 v193, v161, v129
	v_fmac_f32_e32 v194, v154, v110
	v_fmac_f32_e32 v195, v155, v111
	v_fmac_f32_e32 v196, v156, v112
	v_fmac_f32_e32 v197, v157, v113
	v_fmac_f32_e32 v190, v142, v114
	v_fmac_f32_e32 v191, v143, v115
	v_fmac_f32_e32 v192, v144, v116
	v_fmac_f32_e32 v193, v145, v117
	v_fmac_f32_e32 v194, v138, v98
	v_fmac_f32_e32 v195, v139, v99
	v_fmac_f32_e32 v196, v140, v100
	v_fmac_f32_e32 v197, v141, v101
	v_cmp_gt_i32_e32 vcc, s3, v228
	v_mul_f32_e32 v198, 0xbfb8aa3b, v190
	v_mul_f32_e32 v199, 0xbfb8aa3b, v191
	v_mul_f32_e32 v200, 0xbfb8aa3b, v192
	v_mul_f32_e32 v201, 0xbfb8aa3b, v193
	v_exp_f32_e32 v198, v198
	v_exp_f32_e32 v199, v199
	v_exp_f32_e32 v200, v200
	v_exp_f32_e32 v201, v201
	v_add_f32_e32 v198, 1.0, v198
	v_add_f32_e32 v199, 1.0, v199
	v_add_f32_e32 v200, 1.0, v200
	v_add_f32_e32 v201, 1.0, v201
	v_rcp_f32_e32 v198, v198
	v_rcp_f32_e32 v199, v199
	v_rcp_f32_e32 v200, v200
	v_rcp_f32_e32 v201, v201
	v_mul_f32_e32 v190, v190, v198
	v_mul_f32_e32 v191, v191, v199
	v_mul_f32_e32 v192, v192, v200
	v_mul_f32_e32 v193, v193, v201
	v_mul_f32_e32 v190, v190, v194
	v_mul_f32_e32 v191, v191, v195
	v_mul_f32_e32 v192, v192, v196
	v_mul_f32_e32 v193, v193, v197
	v_cvt_pk_bf16_f32 v226, v190, v191
	v_cvt_pk_bf16_f32 v227, v192, v193
	s_and_saveexec_b64 s[0:1], vcc
	global_store_dwordx2 v229, v[226:227], s[12:13]
	s_mov_b64 exec, s[0:1]
	v_fma_f32 v190, v142, v122, v118
	v_fma_f32 v191, v143, v123, v119
	v_fma_f32 v192, v144, v124, v120
	v_fma_f32 v193, v145, v125, v121
	v_fma_f32 v194, v138, v106, v102
	v_fma_f32 v195, v139, v107, v103
	v_fma_f32 v196, v140, v108, v104
	v_fma_f32 v197, v141, v109, v105
	v_add_u32_e32 v228, 2, v186
	v_add_u32_e32 v229, 0x2c00, v187
	v_fmac_f32_e32 v190, v150, v126
	v_fmac_f32_e32 v191, v151, v127
	v_fmac_f32_e32 v192, v152, v128
	v_fmac_f32_e32 v193, v153, v129
	v_fmac_f32_e32 v194, v146, v110
	v_fmac_f32_e32 v195, v147, v111
	v_fmac_f32_e32 v196, v148, v112
	v_fmac_f32_e32 v197, v149, v113
	v_fmac_f32_e32 v190, v134, v114
	v_fmac_f32_e32 v191, v135, v115
	v_fmac_f32_e32 v192, v136, v116
	v_fmac_f32_e32 v193, v137, v117
	v_fmac_f32_e32 v194, v130, v98
	v_fmac_f32_e32 v195, v131, v99
	v_fmac_f32_e32 v196, v132, v100
	v_fmac_f32_e32 v197, v133, v101
	v_cmp_gt_i32_e32 vcc, s3, v228
	v_mul_f32_e32 v198, 0xbfb8aa3b, v190
	v_mul_f32_e32 v199, 0xbfb8aa3b, v191
	v_mul_f32_e32 v200, 0xbfb8aa3b, v192
	v_mul_f32_e32 v201, 0xbfb8aa3b, v193
	v_exp_f32_e32 v198, v198
	v_exp_f32_e32 v199, v199
	v_exp_f32_e32 v200, v200
	v_exp_f32_e32 v201, v201
	v_add_f32_e32 v198, 1.0, v198
	v_add_f32_e32 v199, 1.0, v199
	v_add_f32_e32 v200, 1.0, v200
	v_add_f32_e32 v201, 1.0, v201
	v_rcp_f32_e32 v198, v198
	v_rcp_f32_e32 v199, v199
	v_rcp_f32_e32 v200, v200
	v_rcp_f32_e32 v201, v201
	v_mul_f32_e32 v190, v190, v198
	v_mul_f32_e32 v191, v191, v199
	v_mul_f32_e32 v192, v192, v200
	v_mul_f32_e32 v193, v193, v201
	v_mul_f32_e32 v190, v190, v194
	v_mul_f32_e32 v191, v191, v195
	v_mul_f32_e32 v192, v192, v196
	v_mul_f32_e32 v193, v193, v197
	v_cvt_pk_bf16_f32 v226, v190, v191
	v_cvt_pk_bf16_f32 v227, v192, v193
	s_and_saveexec_b64 s[0:1], vcc
	global_store_dwordx2 v229, v[226:227], s[12:13]
	s_mov_b64 exec, s[0:1]
	v_fma_f32 v190, v134, v122, v118
	v_fma_f32 v191, v135, v123, v119
	v_fma_f32 v192, v136, v124, v120
	v_fma_f32 v193, v137, v125, v121
	v_fma_f32 v194, v130, v106, v102
	v_fma_f32 v195, v131, v107, v103
	v_fma_f32 v196, v132, v108, v104
	v_fma_f32 v197, v133, v109, v105
	v_add_u32_e32 v228, 3, v186
	v_add_u32_e32 v229, 0x4200, v187
	v_fmac_f32_e32 v190, v142, v126
	v_fmac_f32_e32 v191, v143, v127
	v_fmac_f32_e32 v192, v144, v128
	v_fmac_f32_e32 v193, v145, v129
	v_fmac_f32_e32 v194, v138, v110
	v_fmac_f32_e32 v195, v139, v111
	v_fmac_f32_e32 v196, v140, v112
	v_fmac_f32_e32 v197, v141, v113
	v_fmac_f32_dpp v190, v158, v114 row_ror:15 row_mask:0xf bank_mask:0xf
	v_fmac_f32_dpp v191, v159, v115 row_ror:15 row_mask:0xf bank_mask:0xf
	v_fmac_f32_dpp v192, v160, v116 row_ror:15 row_mask:0xf bank_mask:0xf
	v_fmac_f32_dpp v193, v161, v117 row_ror:15 row_mask:0xf bank_mask:0xf
	v_fmac_f32_dpp v194, v154, v98 row_ror:15 row_mask:0xf bank_mask:0xf
	v_fmac_f32_dpp v195, v155, v99 row_ror:15 row_mask:0xf bank_mask:0xf
	v_fmac_f32_dpp v196, v156, v100 row_ror:15 row_mask:0xf bank_mask:0xf
	v_fmac_f32_dpp v197, v157, v101 row_ror:15 row_mask:0xf bank_mask:0xf
	v_cmp_gt_i32_e32 vcc, s3, v228
	v_mul_f32_e32 v198, 0xbfb8aa3b, v190
	v_mul_f32_e32 v199, 0xbfb8aa3b, v191
	v_mul_f32_e32 v200, 0xbfb8aa3b, v192
	v_mul_f32_e32 v201, 0xbfb8aa3b, v193
	v_exp_f32_e32 v198, v198
	v_exp_f32_e32 v199, v199
	v_exp_f32_e32 v200, v200
	v_exp_f32_e32 v201, v201
	v_add_f32_e32 v198, 1.0, v198
	v_add_f32_e32 v199, 1.0, v199
	v_add_f32_e32 v200, 1.0, v200
	v_add_f32_e32 v201, 1.0, v201
	v_rcp_f32_e32 v198, v198
	v_rcp_f32_e32 v199, v199
	v_rcp_f32_e32 v200, v200
	v_rcp_f32_e32 v201, v201
	v_mul_f32_e32 v190, v190, v198
	v_mul_f32_e32 v191, v191, v199
	v_mul_f32_e32 v192, v192, v200
	v_mul_f32_e32 v193, v193, v201
	v_mul_f32_e32 v190, v190, v194
	v_mul_f32_e32 v191, v191, v195
	v_mul_f32_e32 v192, v192, v196
	v_mul_f32_e32 v193, v193, v197
	v_cvt_pk_bf16_f32 v226, v190, v191
	v_cvt_pk_bf16_f32 v227, v192, v193
	s_and_b64 vcc, vcc, s[44:45]
	s_and_saveexec_b64 s[0:1], vcc
	global_store_dwordx2 v229, v[226:227], s[12:13]
	s_mov_b64 exec, s[0:1]
	ds_read_b128 v[130:133], v188 offset:64
	ds_read_b128 v[134:137], v188 offset:192
	ds_read_b128 v[138:141], v188 offset:320
	ds_read_b128 v[142:145], v188 offset:448
	ds_read_b128 v[146:149], v188 offset:576
	ds_read_b128 v[150:153], v188 offset:704
	ds_read_b128 v[154:157], v188 offset:832
	ds_read_b128 v[158:161], v188 offset:960
	v_fma_f32 v190, v94, v122, v118
	v_fma_f32 v191, v95, v123, v119
	v_fma_f32 v192, v96, v124, v120
	v_fma_f32 v193, v97, v125, v121
	v_fma_f32 v194, v90, v106, v102
	v_fma_f32 v195, v91, v107, v103
	v_fma_f32 v196, v92, v108, v104
	v_fma_f32 v197, v93, v109, v105
	v_add_u32_e32 v228, 0x7c, v186
	v_add_u32_e32 v229, 0xaa800, v187
	v_fmac_f32_dpp v190, v70, v126 row_ror:1 row_mask:0xf bank_mask:0xf
	v_fmac_f32_dpp v191, v71, v127 row_ror:1 row_mask:0xf bank_mask:0xf
	v_fmac_f32_dpp v192, v72, v128 row_ror:1 row_mask:0xf bank_mask:0xf
	v_fmac_f32_dpp v193, v73, v129 row_ror:1 row_mask:0xf bank_mask:0xf
	v_fmac_f32_dpp v194, v66, v110 row_ror:1 row_mask:0xf bank_mask:0xf
	v_fmac_f32_dpp v195, v67, v111 row_ror:1 row_mask:0xf bank_mask:0xf
	v_fmac_f32_dpp v196, v68, v112 row_ror:1 row_mask:0xf bank_mask:0xf
	v_fmac_f32_dpp v197, v69, v113 row_ror:1 row_mask:0xf bank_mask:0xf
	v_fmac_f32_e32 v190, v86, v114
	v_fmac_f32_e32 v191, v87, v115
	v_fmac_f32_e32 v192, v88, v116
	v_fmac_f32_e32 v193, v89, v117
	v_fmac_f32_e32 v194, v82, v98
	v_fmac_f32_e32 v195, v83, v99
	v_fmac_f32_e32 v196, v84, v100
	v_fmac_f32_e32 v197, v85, v101
	v_cmp_gt_i32_e32 vcc, s3, v228
	v_mul_f32_e32 v198, 0xbfb8aa3b, v190
	v_mul_f32_e32 v199, 0xbfb8aa3b, v191
	v_mul_f32_e32 v200, 0xbfb8aa3b, v192
	v_mul_f32_e32 v201, 0xbfb8aa3b, v193
	v_exp_f32_e32 v198, v198
	v_exp_f32_e32 v199, v199
	v_exp_f32_e32 v200, v200
	v_exp_f32_e32 v201, v201
	v_add_f32_e32 v198, 1.0, v198
	v_add_f32_e32 v199, 1.0, v199
	v_add_f32_e32 v200, 1.0, v200
	v_add_f32_e32 v201, 1.0, v201
	v_rcp_f32_e32 v198, v198
	v_rcp_f32_e32 v199, v199
	v_rcp_f32_e32 v200, v200
	v_rcp_f32_e32 v201, v201
	v_mul_f32_e32 v190, v190, v198
	v_mul_f32_e32 v191, v191, v199
	v_mul_f32_e32 v192, v192, v200
	v_mul_f32_e32 v193, v193, v201
	v_mul_f32_e32 v190, v190, v194
	v_mul_f32_e32 v191, v191, v195
	v_mul_f32_e32 v192, v192, v196
	v_mul_f32_e32 v193, v193, v197
	v_cvt_pk_bf16_f32 v226, v190, v191
	v_cvt_pk_bf16_f32 v227, v192, v193
	s_and_b64 vcc, vcc, s[42:43]
	s_and_saveexec_b64 s[0:1], vcc
	global_store_dwordx2 v229, v[226:227], s[12:13]
	s_mov_b64 exec, s[0:1]
	v_fma_f32 v190, v86, v122, v118
	v_fma_f32 v191, v87, v123, v119
	v_fma_f32 v192, v88, v124, v120
	v_fma_f32 v193, v89, v125, v121
	v_fma_f32 v194, v82, v106, v102
	v_fma_f32 v195, v83, v107, v103
	v_fma_f32 v196, v84, v108, v104
	v_fma_f32 v197, v85, v109, v105
	v_add_u32_e32 v228, 0x7d, v186
	v_add_u32_e32 v229, 0xabe00, v187
	v_fmac_f32_e32 v190, v94, v126
	v_fmac_f32_e32 v191, v95, v127
	v_fmac_f32_e32 v192, v96, v128
	v_fmac_f32_e32 v193, v97, v129
	v_fmac_f32_e32 v194, v90, v110
	v_fmac_f32_e32 v195, v91, v111
	v_fmac_f32_e32 v196, v92, v112
	v_fmac_f32_e32 v197, v93, v113
	v_fmac_f32_e32 v190, v78, v114
	v_fmac_f32_e32 v191, v79, v115
	v_fmac_f32_e32 v192, v80, v116
	v_fmac_f32_e32 v193, v81, v117
	v_fmac_f32_e32 v194, v74, v98
	v_fmac_f32_e32 v195, v75, v99
	v_fmac_f32_e32 v196, v76, v100
	v_fmac_f32_e32 v197, v77, v101
	v_cmp_gt_i32_e32 vcc, s3, v228
	v_mul_f32_e32 v198, 0xbfb8aa3b, v190
	v_mul_f32_e32 v199, 0xbfb8aa3b, v191
	v_mul_f32_e32 v200, 0xbfb8aa3b, v192
	v_mul_f32_e32 v201, 0xbfb8aa3b, v193
	v_exp_f32_e32 v198, v198
	v_exp_f32_e32 v199, v199
	v_exp_f32_e32 v200, v200
	v_exp_f32_e32 v201, v201
	v_add_f32_e32 v198, 1.0, v198
	v_add_f32_e32 v199, 1.0, v199
	v_add_f32_e32 v200, 1.0, v200
	v_add_f32_e32 v201, 1.0, v201
	v_rcp_f32_e32 v198, v198
	v_rcp_f32_e32 v199, v199
	v_rcp_f32_e32 v200, v200
	v_rcp_f32_e32 v201, v201
	v_mul_f32_e32 v190, v190, v198
	v_mul_f32_e32 v191, v191, v199
	v_mul_f32_e32 v192, v192, v200
	v_mul_f32_e32 v193, v193, v201
	v_mul_f32_e32 v190, v190, v194
	v_mul_f32_e32 v191, v191, v195
	v_mul_f32_e32 v192, v192, v196
	v_mul_f32_e32 v193, v193, v197
	v_cvt_pk_bf16_f32 v226, v190, v191
	v_cvt_pk_bf16_f32 v227, v192, v193
	s_and_saveexec_b64 s[0:1], vcc
	global_store_dwordx2 v229, v[226:227], s[12:13]
	s_mov_b64 exec, s[0:1]
	v_fma_f32 v190, v78, v122, v118
	v_fma_f32 v191, v79, v123, v119
	v_fma_f32 v192, v80, v124, v120
	v_fma_f32 v193, v81, v125, v121
	v_fma_f32 v194, v74, v106, v102
	v_fma_f32 v195, v75, v107, v103
	v_fma_f32 v196, v76, v108, v104
	v_fma_f32 v197, v77, v109, v105
	v_add_u32_e32 v228, 0x7e, v186
	v_add_u32_e32 v229, 0xad400, v187
	v_fmac_f32_e32 v190, v86, v126
	v_fmac_f32_e32 v191, v87, v127
	v_fmac_f32_e32 v192, v88, v128
	v_fmac_f32_e32 v193, v89, v129
	v_fmac_f32_e32 v194, v82, v110
	v_fmac_f32_e32 v195, v83, v111
	v_fmac_f32_e32 v196, v84, v112
	v_fmac_f32_e32 v197, v85, v113
	v_fmac_f32_e32 v190, v70, v114
	v_fmac_f32_e32 v191, v71, v115
	v_fmac_f32_e32 v192, v72, v116
	v_fmac_f32_e32 v193, v73, v117
	v_fmac_f32_e32 v194, v66, v98
	v_fmac_f32_e32 v195, v67, v99
	v_fmac_f32_e32 v196, v68, v100
	v_fmac_f32_e32 v197, v69, v101
	v_cmp_gt_i32_e32 vcc, s3, v228
	v_mul_f32_e32 v198, 0xbfb8aa3b, v190
	v_mul_f32_e32 v199, 0xbfb8aa3b, v191
	v_mul_f32_e32 v200, 0xbfb8aa3b, v192
	v_mul_f32_e32 v201, 0xbfb8aa3b, v193
	v_exp_f32_e32 v198, v198
	v_exp_f32_e32 v199, v199
	v_exp_f32_e32 v200, v200
	v_exp_f32_e32 v201, v201
	v_add_f32_e32 v198, 1.0, v198
	v_add_f32_e32 v199, 1.0, v199
	v_add_f32_e32 v200, 1.0, v200
	v_add_f32_e32 v201, 1.0, v201
	v_rcp_f32_e32 v198, v198
	v_rcp_f32_e32 v199, v199
	v_rcp_f32_e32 v200, v200
	v_rcp_f32_e32 v201, v201
	v_mul_f32_e32 v190, v190, v198
	v_mul_f32_e32 v191, v191, v199
	v_mul_f32_e32 v192, v192, v200
	v_mul_f32_e32 v193, v193, v201
	v_mul_f32_e32 v190, v190, v194
	v_mul_f32_e32 v191, v191, v195
	v_mul_f32_e32 v192, v192, v196
	v_mul_f32_e32 v193, v193, v197
	v_cvt_pk_bf16_f32 v226, v190, v191
	v_cvt_pk_bf16_f32 v227, v192, v193
	s_and_saveexec_b64 s[0:1], vcc
	global_store_dwordx2 v229, v[226:227], s[12:13]
	s_mov_b64 exec, s[0:1]
	v_fma_f32 v190, v70, v122, v118
	v_fma_f32 v191, v71, v123, v119
	v_fma_f32 v192, v72, v124, v120
	v_fma_f32 v193, v73, v125, v121
	v_fma_f32 v194, v66, v106, v102
	v_fma_f32 v195, v67, v107, v103
	v_fma_f32 v196, v68, v108, v104
	v_fma_f32 v197, v69, v109, v105
	v_add_u32_e32 v228, 0x7f, v186
	v_add_u32_e32 v229, 0xaea00, v187
	v_fmac_f32_e32 v190, v78, v126
	v_fmac_f32_e32 v191, v79, v127
	v_fmac_f32_e32 v192, v80, v128
	v_fmac_f32_e32 v193, v81, v129
	v_fmac_f32_e32 v194, v74, v110
	v_fmac_f32_e32 v195, v75, v111
	v_fmac_f32_e32 v196, v76, v112
	v_fmac_f32_e32 v197, v77, v113
	v_fmac_f32_dpp v190, v94, v114 row_ror:15 row_mask:0xf bank_mask:0xf
	v_fmac_f32_dpp v191, v95, v115 row_ror:15 row_mask:0xf bank_mask:0xf
	v_fmac_f32_dpp v192, v96, v116 row_ror:15 row_mask:0xf bank_mask:0xf
	v_fmac_f32_dpp v193, v97, v117 row_ror:15 row_mask:0xf bank_mask:0xf
	v_fmac_f32_dpp v194, v90, v98 row_ror:15 row_mask:0xf bank_mask:0xf
	v_fmac_f32_dpp v195, v91, v99 row_ror:15 row_mask:0xf bank_mask:0xf
	v_fmac_f32_dpp v196, v92, v100 row_ror:15 row_mask:0xf bank_mask:0xf
	v_fmac_f32_dpp v197, v93, v101 row_ror:15 row_mask:0xf bank_mask:0xf
	v_cmp_gt_i32_e32 vcc, s3, v228
	v_mul_f32_e32 v198, 0xbfb8aa3b, v190
	v_mul_f32_e32 v199, 0xbfb8aa3b, v191
	v_mul_f32_e32 v200, 0xbfb8aa3b, v192
	v_mul_f32_e32 v201, 0xbfb8aa3b, v193
	v_exp_f32_e32 v198, v198
	v_exp_f32_e32 v199, v199
	v_exp_f32_e32 v200, v200
	v_exp_f32_e32 v201, v201
	v_add_f32_e32 v198, 1.0, v198
	v_add_f32_e32 v199, 1.0, v199
	v_add_f32_e32 v200, 1.0, v200
	v_add_f32_e32 v201, 1.0, v201
	v_rcp_f32_e32 v198, v198
	v_rcp_f32_e32 v199, v199
	v_rcp_f32_e32 v200, v200
	v_rcp_f32_e32 v201, v201
	v_mul_f32_e32 v190, v190, v198
	v_mul_f32_e32 v191, v191, v199
	v_mul_f32_e32 v192, v192, v200
	v_mul_f32_e32 v193, v193, v201
	v_mul_f32_e32 v190, v190, v194
	v_mul_f32_e32 v191, v191, v195
	v_mul_f32_e32 v192, v192, v196
	v_mul_f32_e32 v193, v193, v197
	v_cvt_pk_bf16_f32 v226, v190, v191
	v_cvt_pk_bf16_f32 v227, v192, v193
	s_and_b64 vcc, vcc, s[44:45]
	s_and_saveexec_b64 s[0:1], vcc
	global_store_dwordx2 v229, v[226:227], s[12:13]
	s_mov_b64 exec, s[0:1]
	s_waitcnt lgkmcnt(0)
	v_fma_f32 v190, v62, v134, v142
	v_fma_f32 v191, v63, v135, v143
	v_fma_f32 v192, v64, v136, v144
	v_fma_f32 v193, v65, v137, v145
	v_fma_f32 v194, v58, v150, v158
	v_fma_f32 v195, v59, v151, v159
	v_fma_f32 v196, v60, v152, v160
	v_fma_f32 v197, v61, v153, v161
	v_add_u32_e32 v228, 0, v186
	v_fmac_f32_dpp v190, v38, v130 row_ror:1 row_mask:0xf bank_mask:0xf
	v_fmac_f32_dpp v191, v39, v131 row_ror:1 row_mask:0xf bank_mask:0xf
	v_fmac_f32_dpp v192, v40, v132 row_ror:1 row_mask:0xf bank_mask:0xf
	v_fmac_f32_dpp v193, v41, v133 row_ror:1 row_mask:0xf bank_mask:0xf
	v_fmac_f32_dpp v194, v34, v146 row_ror:1 row_mask:0xf bank_mask:0xf
	v_fmac_f32_dpp v195, v35, v147 row_ror:1 row_mask:0xf bank_mask:0xf
	v_fmac_f32_dpp v196, v36, v148 row_ror:1 row_mask:0xf bank_mask:0xf
	v_fmac_f32_dpp v197, v37, v149 row_ror:1 row_mask:0xf bank_mask:0xf
	v_fmac_f32_e32 v190, v54, v138
	v_fmac_f32_e32 v191, v55, v139
	v_fmac_f32_e32 v192, v56, v140
	v_fmac_f32_e32 v193, v57, v141
	v_fmac_f32_e32 v194, v50, v154
	v_fmac_f32_e32 v195, v51, v155
	v_fmac_f32_e32 v196, v52, v156
	v_fmac_f32_e32 v197, v53, v157
	v_cmp_gt_i32_e32 vcc, s3, v228
	v_mul_f32_e32 v198, 0xbfb8aa3b, v190
	v_mul_f32_e32 v199, 0xbfb8aa3b, v191
	v_mul_f32_e32 v200, 0xbfb8aa3b, v192
	v_mul_f32_e32 v201, 0xbfb8aa3b, v193
	v_exp_f32_e32 v198, v198
	v_exp_f32_e32 v199, v199
	v_exp_f32_e32 v200, v200
	v_exp_f32_e32 v201, v201
	v_add_f32_e32 v198, 1.0, v198
	v_add_f32_e32 v199, 1.0, v199
	v_add_f32_e32 v200, 1.0, v200
	v_add_f32_e32 v201, 1.0, v201
	v_rcp_f32_e32 v198, v198
	v_rcp_f32_e32 v199, v199
	v_rcp_f32_e32 v200, v200
	v_rcp_f32_e32 v201, v201
	v_mul_f32_e32 v190, v190, v198
	v_mul_f32_e32 v191, v191, v199
	v_mul_f32_e32 v192, v192, v200
	v_mul_f32_e32 v193, v193, v201
	v_mul_f32_e32 v190, v190, v194
	v_mul_f32_e32 v191, v191, v195
	v_mul_f32_e32 v192, v192, v196
	v_mul_f32_e32 v193, v193, v197
	v_cvt_pk_bf16_f32 v226, v190, v191
	v_cvt_pk_bf16_f32 v227, v192, v193
	s_and_b64 vcc, vcc, s[42:43]
	s_and_saveexec_b64 s[0:1], vcc
	global_store_dwordx2 v187, v[226:227], s[12:13] offset:128
	s_mov_b64 exec, s[0:1]
	v_fma_f32 v190, v54, v134, v142
	v_fma_f32 v191, v55, v135, v143
	v_fma_f32 v192, v56, v136, v144
	v_fma_f32 v193, v57, v137, v145
	v_fma_f32 v194, v50, v150, v158
	v_fma_f32 v195, v51, v151, v159
	v_fma_f32 v196, v52, v152, v160
	v_fma_f32 v197, v53, v153, v161
	v_add_u32_e32 v228, 1, v186
	v_add_u32_e32 v229, 0x1600, v187
	v_fmac_f32_e32 v190, v62, v130
	v_fmac_f32_e32 v191, v63, v131
	v_fmac_f32_e32 v192, v64, v132
	v_fmac_f32_e32 v193, v65, v133
	v_fmac_f32_e32 v194, v58, v146
	v_fmac_f32_e32 v195, v59, v147
	v_fmac_f32_e32 v196, v60, v148
	v_fmac_f32_e32 v197, v61, v149
	v_fmac_f32_e32 v190, v46, v138
	v_fmac_f32_e32 v191, v47, v139
	v_fmac_f32_e32 v192, v48, v140
	v_fmac_f32_e32 v193, v49, v141
	v_fmac_f32_e32 v194, v42, v154
	v_fmac_f32_e32 v195, v43, v155
	v_fmac_f32_e32 v196, v44, v156
	v_fmac_f32_e32 v197, v45, v157
	v_cmp_gt_i32_e32 vcc, s3, v228
	v_mul_f32_e32 v198, 0xbfb8aa3b, v190
	v_mul_f32_e32 v199, 0xbfb8aa3b, v191
	v_mul_f32_e32 v200, 0xbfb8aa3b, v192
	v_mul_f32_e32 v201, 0xbfb8aa3b, v193
	v_exp_f32_e32 v198, v198
	v_exp_f32_e32 v199, v199
	v_exp_f32_e32 v200, v200
	v_exp_f32_e32 v201, v201
	v_add_f32_e32 v198, 1.0, v198
	v_add_f32_e32 v199, 1.0, v199
	v_add_f32_e32 v200, 1.0, v200
	v_add_f32_e32 v201, 1.0, v201
	v_rcp_f32_e32 v198, v198
	v_rcp_f32_e32 v199, v199
	v_rcp_f32_e32 v200, v200
	v_rcp_f32_e32 v201, v201
	v_mul_f32_e32 v190, v190, v198
	v_mul_f32_e32 v191, v191, v199
	v_mul_f32_e32 v192, v192, v200
	v_mul_f32_e32 v193, v193, v201
	v_mul_f32_e32 v190, v190, v194
	v_mul_f32_e32 v191, v191, v195
	v_mul_f32_e32 v192, v192, v196
	v_mul_f32_e32 v193, v193, v197
	v_cvt_pk_bf16_f32 v226, v190, v191
	v_cvt_pk_bf16_f32 v227, v192, v193
	s_and_saveexec_b64 s[0:1], vcc
	global_store_dwordx2 v229, v[226:227], s[12:13] offset:128
	s_mov_b64 exec, s[0:1]
	v_fma_f32 v190, v46, v134, v142
	v_fma_f32 v191, v47, v135, v143
	v_fma_f32 v192, v48, v136, v144
	v_fma_f32 v193, v49, v137, v145
	v_fma_f32 v194, v42, v150, v158
	v_fma_f32 v195, v43, v151, v159
	v_fma_f32 v196, v44, v152, v160
	v_fma_f32 v197, v45, v153, v161
	v_add_u32_e32 v228, 2, v186
	v_add_u32_e32 v229, 0x2c00, v187
	v_fmac_f32_e32 v190, v54, v130
	v_fmac_f32_e32 v191, v55, v131
	v_fmac_f32_e32 v192, v56, v132
	v_fmac_f32_e32 v193, v57, v133
	v_fmac_f32_e32 v194, v50, v146
	v_fmac_f32_e32 v195, v51, v147
	v_fmac_f32_e32 v196, v52, v148
	v_fmac_f32_e32 v197, v53, v149
	v_fmac_f32_e32 v190, v38, v138
	v_fmac_f32_e32 v191, v39, v139
	v_fmac_f32_e32 v192, v40, v140
	v_fmac_f32_e32 v193, v41, v141
	v_fmac_f32_e32 v194, v34, v154
	v_fmac_f32_e32 v195, v35, v155
	v_fmac_f32_e32 v196, v36, v156
	v_fmac_f32_e32 v197, v37, v157
	v_cmp_gt_i32_e32 vcc, s3, v228
	v_mul_f32_e32 v198, 0xbfb8aa3b, v190
	v_mul_f32_e32 v199, 0xbfb8aa3b, v191
	v_mul_f32_e32 v200, 0xbfb8aa3b, v192
	v_mul_f32_e32 v201, 0xbfb8aa3b, v193
	v_exp_f32_e32 v198, v198
	v_exp_f32_e32 v199, v199
	v_exp_f32_e32 v200, v200
	v_exp_f32_e32 v201, v201
	v_add_f32_e32 v198, 1.0, v198
	v_add_f32_e32 v199, 1.0, v199
	v_add_f32_e32 v200, 1.0, v200
	v_add_f32_e32 v201, 1.0, v201
	v_rcp_f32_e32 v198, v198
	v_rcp_f32_e32 v199, v199
	v_rcp_f32_e32 v200, v200
	v_rcp_f32_e32 v201, v201
	v_mul_f32_e32 v190, v190, v198
	v_mul_f32_e32 v191, v191, v199
	v_mul_f32_e32 v192, v192, v200
	v_mul_f32_e32 v193, v193, v201
	v_mul_f32_e32 v190, v190, v194
	v_mul_f32_e32 v191, v191, v195
	v_mul_f32_e32 v192, v192, v196
	v_mul_f32_e32 v193, v193, v197
	v_cvt_pk_bf16_f32 v226, v190, v191
	v_cvt_pk_bf16_f32 v227, v192, v193
	s_and_saveexec_b64 s[0:1], vcc
	global_store_dwordx2 v229, v[226:227], s[12:13] offset:128
	s_mov_b64 exec, s[0:1]
	v_fma_f32 v190, v38, v134, v142
	v_fma_f32 v191, v39, v135, v143
	v_fma_f32 v192, v40, v136, v144
	v_fma_f32 v193, v41, v137, v145
	v_fma_f32 v194, v34, v150, v158
	v_fma_f32 v195, v35, v151, v159
	v_fma_f32 v196, v36, v152, v160
	v_fma_f32 v197, v37, v153, v161
	v_add_u32_e32 v228, 3, v186
	v_add_u32_e32 v229, 0x4200, v187
	v_fmac_f32_e32 v190, v46, v130
	v_fmac_f32_e32 v191, v47, v131
	v_fmac_f32_e32 v192, v48, v132
	v_fmac_f32_e32 v193, v49, v133
	v_fmac_f32_e32 v194, v42, v146
	v_fmac_f32_e32 v195, v43, v147
	v_fmac_f32_e32 v196, v44, v148
	v_fmac_f32_e32 v197, v45, v149
	v_fmac_f32_dpp v190, v62, v138 row_ror:15 row_mask:0xf bank_mask:0xf
	v_fmac_f32_dpp v191, v63, v139 row_ror:15 row_mask:0xf bank_mask:0xf
	v_fmac_f32_dpp v192, v64, v140 row_ror:15 row_mask:0xf bank_mask:0xf
	v_fmac_f32_dpp v193, v65, v141 row_ror:15 row_mask:0xf bank_mask:0xf
	v_fmac_f32_dpp v194, v58, v154 row_ror:15 row_mask:0xf bank_mask:0xf
	v_fmac_f32_dpp v195, v59, v155 row_ror:15 row_mask:0xf bank_mask:0xf
	v_fmac_f32_dpp v196, v60, v156 row_ror:15 row_mask:0xf bank_mask:0xf
	v_fmac_f32_dpp v197, v61, v157 row_ror:15 row_mask:0xf bank_mask:0xf
	v_cmp_gt_i32_e32 vcc, s3, v228
	v_mul_f32_e32 v198, 0xbfb8aa3b, v190
	v_mul_f32_e32 v199, 0xbfb8aa3b, v191
	v_mul_f32_e32 v200, 0xbfb8aa3b, v192
	v_mul_f32_e32 v201, 0xbfb8aa3b, v193
	v_exp_f32_e32 v198, v198
	v_exp_f32_e32 v199, v199
	v_exp_f32_e32 v200, v200
	v_exp_f32_e32 v201, v201
	v_add_f32_e32 v198, 1.0, v198
	v_add_f32_e32 v199, 1.0, v199
	v_add_f32_e32 v200, 1.0, v200
	v_add_f32_e32 v201, 1.0, v201
	v_rcp_f32_e32 v198, v198
	v_rcp_f32_e32 v199, v199
	v_rcp_f32_e32 v200, v200
	v_rcp_f32_e32 v201, v201
	v_mul_f32_e32 v190, v190, v198
	v_mul_f32_e32 v191, v191, v199
	v_mul_f32_e32 v192, v192, v200
	v_mul_f32_e32 v193, v193, v201
	v_mul_f32_e32 v190, v190, v194
	v_mul_f32_e32 v191, v191, v195
	v_mul_f32_e32 v192, v192, v196
	v_mul_f32_e32 v193, v193, v197
	v_cvt_pk_bf16_f32 v226, v190, v191
	v_cvt_pk_bf16_f32 v227, v192, v193
	s_and_b64 vcc, vcc, s[44:45]
	s_and_saveexec_b64 s[0:1], vcc
	global_store_dwordx2 v229, v[226:227], s[12:13] offset:128
	s_mov_b64 exec, s[0:1]
	v_fma_f32 v190, v30, v134, v142
	v_fma_f32 v191, v31, v135, v143
	v_fma_f32 v192, v32, v136, v144
	v_fma_f32 v193, v33, v137, v145
	v_fma_f32 v194, v26, v150, v158
	v_fma_f32 v195, v27, v151, v159
	v_fma_f32 v196, v28, v152, v160
	v_fma_f32 v197, v29, v153, v161
	v_add_u32_e32 v228, 0x7c, v186
	v_add_u32_e32 v229, 0xaa800, v187
	v_fmac_f32_dpp v190, v6, v130 row_ror:1 row_mask:0xf bank_mask:0xf
	v_fmac_f32_dpp v191, v7, v131 row_ror:1 row_mask:0xf bank_mask:0xf
	v_fmac_f32_dpp v192, v8, v132 row_ror:1 row_mask:0xf bank_mask:0xf
	v_fmac_f32_dpp v193, v9, v133 row_ror:1 row_mask:0xf bank_mask:0xf
	v_fmac_f32_dpp v194, v2, v146 row_ror:1 row_mask:0xf bank_mask:0xf
	v_fmac_f32_dpp v195, v3, v147 row_ror:1 row_mask:0xf bank_mask:0xf
	v_fmac_f32_dpp v196, v4, v148 row_ror:1 row_mask:0xf bank_mask:0xf
	v_fmac_f32_dpp v197, v5, v149 row_ror:1 row_mask:0xf bank_mask:0xf
	v_fmac_f32_e32 v190, v22, v138
	v_fmac_f32_e32 v191, v23, v139
	v_fmac_f32_e32 v192, v24, v140
	v_fmac_f32_e32 v193, v25, v141
	v_fmac_f32_e32 v194, v18, v154
	v_fmac_f32_e32 v195, v19, v155
	v_fmac_f32_e32 v196, v20, v156
	v_fmac_f32_e32 v197, v21, v157
	v_cmp_gt_i32_e32 vcc, s3, v228
	v_mul_f32_e32 v198, 0xbfb8aa3b, v190
	v_mul_f32_e32 v199, 0xbfb8aa3b, v191
	v_mul_f32_e32 v200, 0xbfb8aa3b, v192
	v_mul_f32_e32 v201, 0xbfb8aa3b, v193
	v_exp_f32_e32 v198, v198
	v_exp_f32_e32 v199, v199
	v_exp_f32_e32 v200, v200
	v_exp_f32_e32 v201, v201
	v_add_f32_e32 v198, 1.0, v198
	v_add_f32_e32 v199, 1.0, v199
	v_add_f32_e32 v200, 1.0, v200
	v_add_f32_e32 v201, 1.0, v201
	v_rcp_f32_e32 v198, v198
	v_rcp_f32_e32 v199, v199
	v_rcp_f32_e32 v200, v200
	v_rcp_f32_e32 v201, v201
	v_mul_f32_e32 v190, v190, v198
	v_mul_f32_e32 v191, v191, v199
	v_mul_f32_e32 v192, v192, v200
	v_mul_f32_e32 v193, v193, v201
	v_mul_f32_e32 v190, v190, v194
	v_mul_f32_e32 v191, v191, v195
	v_mul_f32_e32 v192, v192, v196
	v_mul_f32_e32 v193, v193, v197
	v_cvt_pk_bf16_f32 v226, v190, v191
	v_cvt_pk_bf16_f32 v227, v192, v193
	s_and_b64 vcc, vcc, s[42:43]
	s_and_saveexec_b64 s[0:1], vcc
	global_store_dwordx2 v229, v[226:227], s[12:13] offset:128
	s_mov_b64 exec, s[0:1]
	v_fma_f32 v190, v22, v134, v142
	v_fma_f32 v191, v23, v135, v143
	v_fma_f32 v192, v24, v136, v144
	v_fma_f32 v193, v25, v137, v145
	v_fma_f32 v194, v18, v150, v158
	v_fma_f32 v195, v19, v151, v159
	v_fma_f32 v196, v20, v152, v160
	v_fma_f32 v197, v21, v153, v161
	v_add_u32_e32 v228, 0x7d, v186
	v_add_u32_e32 v229, 0xabe00, v187
	v_fmac_f32_e32 v190, v30, v130
	v_fmac_f32_e32 v191, v31, v131
	v_fmac_f32_e32 v192, v32, v132
	v_fmac_f32_e32 v193, v33, v133
	v_fmac_f32_e32 v194, v26, v146
	v_fmac_f32_e32 v195, v27, v147
	v_fmac_f32_e32 v196, v28, v148
	v_fmac_f32_e32 v197, v29, v149
	v_fmac_f32_e32 v190, v14, v138
	v_fmac_f32_e32 v191, v15, v139
	v_fmac_f32_e32 v192, v16, v140
	v_fmac_f32_e32 v193, v17, v141
	v_fmac_f32_e32 v194, v10, v154
	v_fmac_f32_e32 v195, v11, v155
	v_fmac_f32_e32 v196, v12, v156
	v_fmac_f32_e32 v197, v13, v157
	v_cmp_gt_i32_e32 vcc, s3, v228
	v_mul_f32_e32 v198, 0xbfb8aa3b, v190
	v_mul_f32_e32 v199, 0xbfb8aa3b, v191
	v_mul_f32_e32 v200, 0xbfb8aa3b, v192
	v_mul_f32_e32 v201, 0xbfb8aa3b, v193
	v_exp_f32_e32 v198, v198
	v_exp_f32_e32 v199, v199
	v_exp_f32_e32 v200, v200
	v_exp_f32_e32 v201, v201
	v_add_f32_e32 v198, 1.0, v198
	v_add_f32_e32 v199, 1.0, v199
	v_add_f32_e32 v200, 1.0, v200
	v_add_f32_e32 v201, 1.0, v201
	v_rcp_f32_e32 v198, v198
	v_rcp_f32_e32 v199, v199
	v_rcp_f32_e32 v200, v200
	v_rcp_f32_e32 v201, v201
	v_mul_f32_e32 v190, v190, v198
	v_mul_f32_e32 v191, v191, v199
	v_mul_f32_e32 v192, v192, v200
	v_mul_f32_e32 v193, v193, v201
	v_mul_f32_e32 v190, v190, v194
	v_mul_f32_e32 v191, v191, v195
	v_mul_f32_e32 v192, v192, v196
	v_mul_f32_e32 v193, v193, v197
	v_cvt_pk_bf16_f32 v226, v190, v191
	v_cvt_pk_bf16_f32 v227, v192, v193
	s_and_saveexec_b64 s[0:1], vcc
	global_store_dwordx2 v229, v[226:227], s[12:13] offset:128
	s_mov_b64 exec, s[0:1]
	v_fma_f32 v190, v14, v134, v142
	v_fma_f32 v191, v15, v135, v143
	v_fma_f32 v192, v16, v136, v144
	v_fma_f32 v193, v17, v137, v145
	v_fma_f32 v194, v10, v150, v158
	v_fma_f32 v195, v11, v151, v159
	v_fma_f32 v196, v12, v152, v160
	v_fma_f32 v197, v13, v153, v161
	v_add_u32_e32 v228, 0x7e, v186
	v_add_u32_e32 v229, 0xad400, v187
	v_fmac_f32_e32 v190, v22, v130
	v_fmac_f32_e32 v191, v23, v131
	v_fmac_f32_e32 v192, v24, v132
	v_fmac_f32_e32 v193, v25, v133
	v_fmac_f32_e32 v194, v18, v146
	v_fmac_f32_e32 v195, v19, v147
	v_fmac_f32_e32 v196, v20, v148
	v_fmac_f32_e32 v197, v21, v149
	v_fmac_f32_e32 v190, v6, v138
	v_fmac_f32_e32 v191, v7, v139
	v_fmac_f32_e32 v192, v8, v140
	v_fmac_f32_e32 v193, v9, v141
	v_fmac_f32_e32 v194, v2, v154
	v_fmac_f32_e32 v195, v3, v155
	v_fmac_f32_e32 v196, v4, v156
	v_fmac_f32_e32 v197, v5, v157
	v_cmp_gt_i32_e32 vcc, s3, v228
	v_mul_f32_e32 v198, 0xbfb8aa3b, v190
	v_mul_f32_e32 v199, 0xbfb8aa3b, v191
	v_mul_f32_e32 v200, 0xbfb8aa3b, v192
	v_mul_f32_e32 v201, 0xbfb8aa3b, v193
	v_exp_f32_e32 v198, v198
	v_exp_f32_e32 v199, v199
	v_exp_f32_e32 v200, v200
	v_exp_f32_e32 v201, v201
	v_add_f32_e32 v198, 1.0, v198
	v_add_f32_e32 v199, 1.0, v199
	v_add_f32_e32 v200, 1.0, v200
	v_add_f32_e32 v201, 1.0, v201
	v_rcp_f32_e32 v198, v198
	v_rcp_f32_e32 v199, v199
	v_rcp_f32_e32 v200, v200
	v_rcp_f32_e32 v201, v201
	v_mul_f32_e32 v190, v190, v198
	v_mul_f32_e32 v191, v191, v199
	v_mul_f32_e32 v192, v192, v200
	v_mul_f32_e32 v193, v193, v201
	v_mul_f32_e32 v190, v190, v194
	v_mul_f32_e32 v191, v191, v195
	v_mul_f32_e32 v192, v192, v196
	v_mul_f32_e32 v193, v193, v197
	v_cvt_pk_bf16_f32 v226, v190, v191
	v_cvt_pk_bf16_f32 v227, v192, v193
	s_and_saveexec_b64 s[0:1], vcc
	global_store_dwordx2 v229, v[226:227], s[12:13] offset:128
	s_mov_b64 exec, s[0:1]
	v_fma_f32 v190, v6, v134, v142
	v_fma_f32 v191, v7, v135, v143
	v_fma_f32 v192, v8, v136, v144
	v_fma_f32 v193, v9, v137, v145
	v_fma_f32 v194, v2, v150, v158
	v_fma_f32 v195, v3, v151, v159
	v_fma_f32 v196, v4, v152, v160
	v_fma_f32 v197, v5, v153, v161
	v_add_u32_e32 v228, 0x7f, v186
	v_add_u32_e32 v229, 0xaea00, v187
	v_fmac_f32_e32 v190, v14, v130
	v_fmac_f32_e32 v191, v15, v131
	v_fmac_f32_e32 v192, v16, v132
	v_fmac_f32_e32 v193, v17, v133
	v_fmac_f32_e32 v194, v10, v146
	v_fmac_f32_e32 v195, v11, v147
	v_fmac_f32_e32 v196, v12, v148
	v_fmac_f32_e32 v197, v13, v149
	v_fmac_f32_dpp v190, v30, v138 row_ror:15 row_mask:0xf bank_mask:0xf
	v_fmac_f32_dpp v191, v31, v139 row_ror:15 row_mask:0xf bank_mask:0xf
	v_fmac_f32_dpp v192, v32, v140 row_ror:15 row_mask:0xf bank_mask:0xf
	v_fmac_f32_dpp v193, v33, v141 row_ror:15 row_mask:0xf bank_mask:0xf
	v_fmac_f32_dpp v194, v26, v154 row_ror:15 row_mask:0xf bank_mask:0xf
	v_fmac_f32_dpp v195, v27, v155 row_ror:15 row_mask:0xf bank_mask:0xf
	v_fmac_f32_dpp v196, v28, v156 row_ror:15 row_mask:0xf bank_mask:0xf
	v_fmac_f32_dpp v197, v29, v157 row_ror:15 row_mask:0xf bank_mask:0xf
	v_cmp_gt_i32_e32 vcc, s3, v228
	v_mul_f32_e32 v198, 0xbfb8aa3b, v190
	v_mul_f32_e32 v199, 0xbfb8aa3b, v191
	v_mul_f32_e32 v200, 0xbfb8aa3b, v192
	v_mul_f32_e32 v201, 0xbfb8aa3b, v193
	v_exp_f32_e32 v198, v198
	v_exp_f32_e32 v199, v199
	v_exp_f32_e32 v200, v200
	v_exp_f32_e32 v201, v201
	v_add_f32_e32 v198, 1.0, v198
	v_add_f32_e32 v199, 1.0, v199
	v_add_f32_e32 v200, 1.0, v200
	v_add_f32_e32 v201, 1.0, v201
	v_rcp_f32_e32 v198, v198
	v_rcp_f32_e32 v199, v199
	v_rcp_f32_e32 v200, v200
	v_rcp_f32_e32 v201, v201
	v_mul_f32_e32 v190, v190, v198
	v_mul_f32_e32 v191, v191, v199
	v_mul_f32_e32 v192, v192, v200
	v_mul_f32_e32 v193, v193, v201
	v_mul_f32_e32 v190, v190, v194
	v_mul_f32_e32 v191, v191, v195
	v_mul_f32_e32 v192, v192, v196
	v_mul_f32_e32 v193, v193, v197
	v_cvt_pk_bf16_f32 v226, v190, v191
	v_cvt_pk_bf16_f32 v227, v192, v193
	s_and_b64 vcc, vcc, s[44:45]
	s_and_saveexec_b64 s[0:1], vcc
	global_store_dwordx2 v229, v[226:227], s[12:13] offset:128
	s_mov_b64 exec, s[0:1]
